# PREP gates_tiles: the 32 gate-weight rows staged once per workgroup in LDS by DMA (padded rows) instead of every wave re-reading them from global
# baseline (speedup 1.0000x reference)
; __device__ __forceinline__ void gates_tiles(const Frame& F, int l, int wg0) {
;     const int NGW = (F.G - wg0) * NWAVES, gw = NGW - 1 - ((F.bid - wg0) * NWAVES + F.wave), fr = F.lane & 15, fq = F.lane >> 4;
;     const bf16* H = (const bf16*)(F.ws + WS_H); const bf16* WG = (const bf16*)(F.ws + WS_WIN) + ((size_t)l * NINP + 3072) * D;
;     for (int rt = gw; rt < T / 16; rt += NGW) {
;         f32x4 a0 = {0.f, 0.f, 0.f, 0.f}, a1 = {0.f, 0.f, 0.f, 0.f};
;         const bf16* ap = H + (size_t)(16 * rt + fr) * D + 8 * fq; const bf16* bp = WG + (size_t)fr * D + 8 * fq;
.LBB0_1336:
	s_mov_b64 vcc, 0x400
	v_readlane_b32 s4, v249, 39
	v_readlane_b32 s5, v249, 40
	s_add_u32 s4, s78, s4
	s_addc_u32 s5, s79, s5
	s_add_u32 s4, s4, 0x1e00000
	s_addc_u32 s5, s5, 0
	v_readfirstlane_b32 s6, v0
	s_lshr_b32 s6, s6, 6
	v_and_b32_e32 v68, 63, v0
	v_lshlrev_b32_e32 v68, 4, v68
	v_mov_b32_e32 v69, 0
	s_lshl_b32 s7, s6, 13
	s_add_u32 s4, s4, s7
	s_addc_u32 s5, s5, 0
	v_lshl_add_u64 v[68:69], s[4:5], 0, v[68:69]
	s_mul_i32 s7, s6, 8256
	s_barrier
	s_add_i32 m0, s7, 0
	s_nop 0
	global_load_lds_dwordx4 v[68:69], off
	v_lshl_add_u64 v[68:69], v[68:69], 0, vcc
	s_add_i32 m0, s7, 1024
	s_nop 0
	global_load_lds_dwordx4 v[68:69], off
	v_lshl_add_u64 v[68:69], v[68:69], 0, vcc
	s_add_i32 m0, s7, 2064
	s_nop 0
	global_load_lds_dwordx4 v[68:69], off
	v_lshl_add_u64 v[68:69], v[68:69], 0, vcc
	s_add_i32 m0, s7, 3088
	s_nop 0
	global_load_lds_dwordx4 v[68:69], off
	v_lshl_add_u64 v[68:69], v[68:69], 0, vcc
	s_add_i32 m0, s7, 4128
	s_nop 0
	global_load_lds_dwordx4 v[68:69], off
	v_lshl_add_u64 v[68:69], v[68:69], 0, vcc
	s_add_i32 m0, s7, 5152
	s_nop 0
	global_load_lds_dwordx4 v[68:69], off
	v_lshl_add_u64 v[68:69], v[68:69], 0, vcc
	s_add_i32 m0, s7, 6192
	s_nop 0
	global_load_lds_dwordx4 v[68:69], off
	v_lshl_add_u64 v[68:69], v[68:69], 0, vcc
	s_add_i32 m0, s7, 7216
	s_nop 0
	global_load_lds_dwordx4 v[68:69], off
	s_waitcnt vmcnt(0)
	s_not_b32 s0, s3
	s_add_i32 s3, s75, s0
	s_cmpk_gt_i32 s3, 0x3ff
	s_barrier
	s_cbranch_scc1 .LBB0_1345
	v_and_b32_e32 v198, 48, v1
	v_lshl_add_u64 v[2:3], s[78:79], 0, v[198:199]
	s_mov_b64 s[4:5], 0x6f000000
	s_waitcnt vmcnt(27)
	v_lshl_add_u64 v[10:11], v[2:3], 0, s[4:5]
	v_readlane_b32 s4, v249, 28
	v_cmp_gt_u32_e64 s[0:1], 32, v1
	v_lshlrev_b32_e32 v2, 11, v5
	s_waitcnt vmcnt(20)
	v_add_u32_e32 v1, s4, v24
	s_lshl_b32 s4, s8, 4
	v_subrev_u32_e32 v14, s4, v1
	v_readlane_b32 s4, v249, 39
	v_mov_b32_e32 v3, v199
	v_readlane_b32 s5, v249, 40
	v_and_b32_e32 v198, 48, v0
	v_lshl_add_u64 v[12:13], s[78:79], 0, v[198:199]
	v_lshl_add_u64 v[2:3], s[4:5], 0, v[2:3]
	v_lshl_add_u64 v[2:3], v[2:3], 0, v[198:199]
	v_lshl_add_u64 v[16:17], s[78:79], 0, v[2:3]
	s_branch .LBB0_1339

; __device__ __forceinline__ void gates_tiles(const Frame& F, int l, int wg0) {
;     ...
;     for (int rt = gw; rt < T / 16; rt += NGW) {
;         f32x4 a0 = {0.f, 0.f, 0.f, 0.f}, a1 = {0.f, 0.f, 0.f, 0.f};
;         const bf16* ap = H + (size_t)(16 * rt + fr) * D + 8 * fq; const bf16* bp = WG + (size_t)fr * D + 8 * fq;
; #pragma unroll 8
;         for (int ks = 0; ks < 32; ++ks) { const bf16x8 a = *(const bf16x8*)(ap + 32 * ks), b0 = *(const bf16x8*)(bp + 32 * ks), b1 = *(const bf16x8*)(bp + 16 * D + 32 * ks);
;             a0 = __builtin_amdgcn_mfma_f32_16x16x32_bf16(b0, a, a0, 0, 0, 0); a1 = __builtin_amdgcn_mfma_f32_16x16x32_bf16(b1, a, a1, 0, 0, 0); }
.LBB0_1340:
	v_add_co_u32_e32 v38, vcc, 0x4000000, v18
	s_nop 1
	v_addc_co_u32_e32 v39, vcc, 0, v19, vcc
	v_and_b32_e32 v20, 15, v0
	v_mul_u32_u24_e32 v20, 2064, v20
	v_and_b32_e32 v21, 48, v0
	v_add_u32_e32 v20, v20, v21
	global_load_dwordx4 v[40:43], v[38:39], off
	ds_read_b128 v[44:47], v20
	ds_read_b128 v[48:51], v20 offset:33024
	global_load_dwordx4 v[52:55], v[38:39], off offset:64
	ds_read_b128 v[62:65], v20 offset:64
	ds_read_b128 v[70:73], v20 offset:33088
	global_load_dwordx4 v[82:85], v[38:39], off offset:128
	ds_read_b128 v[86:89], v20 offset:128
	ds_read_b128 v[94:97], v20 offset:33152
	global_load_dwordx4 v[102:105], v[38:39], off offset:192
	ds_read_b128 v[130:133], v20 offset:192
	ds_read_b128 v[134:137], v20 offset:33216
	global_load_dwordx4 v[138:141], v[38:39], off offset:256
	ds_read_b128 v[142:145], v20 offset:256
	ds_read_b128 v[148:151], v20 offset:33280
	s_waitcnt vmcnt(4) lgkmcnt(8)
	v_mfma_f32_16x16x32_bf16 v[6:9], v[44:47], v[40:43], v[6:9]
	v_mfma_f32_16x16x32_bf16 v[2:5], v[48:51], v[40:43], v[2:5]
	global_load_dwordx4 v[40:43], v[38:39], off offset:320
	ds_read_b128 v[44:47], v20 offset:320
	ds_read_b128 v[48:51], v20 offset:33344
	s_waitcnt vmcnt(4) lgkmcnt(8)
	v_mfma_f32_16x16x32_bf16 v[6:9], v[62:65], v[52:55], v[6:9]
	v_mfma_f32_16x16x32_bf16 v[2:5], v[70:73], v[52:55], v[2:5]
	global_load_dwordx4 v[52:55], v[38:39], off offset:384
	ds_read_b128 v[62:65], v20 offset:384
	ds_read_b128 v[70:73], v20 offset:33408
	s_waitcnt vmcnt(4) lgkmcnt(8)
	v_mfma_f32_16x16x32_bf16 v[6:9], v[86:89], v[82:85], v[6:9]
	v_mfma_f32_16x16x32_bf16 v[2:5], v[94:97], v[82:85], v[2:5]
	global_load_dwordx4 v[82:85], v[38:39], off offset:448
	ds_read_b128 v[86:89], v20 offset:448
	ds_read_b128 v[94:97], v20 offset:33472
	s_waitcnt vmcnt(4) lgkmcnt(8)
	v_mfma_f32_16x16x32_bf16 v[6:9], v[130:133], v[102:105], v[6:9]
	v_mfma_f32_16x16x32_bf16 v[2:5], v[134:137], v[102:105], v[2:5]
	global_load_dwordx4 v[102:105], v[38:39], off offset:512
	ds_read_b128 v[130:133], v20 offset:512
	ds_read_b128 v[134:137], v20 offset:33536
	s_waitcnt vmcnt(4) lgkmcnt(8)
	v_mfma_f32_16x16x32_bf16 v[6:9], v[142:145], v[138:141], v[6:9]
	v_mfma_f32_16x16x32_bf16 v[2:5], v[148:151], v[138:141], v[2:5]
	global_load_dwordx4 v[138:141], v[38:39], off offset:576
	ds_read_b128 v[142:145], v20 offset:576
	ds_read_b128 v[148:151], v20 offset:33600
	s_waitcnt vmcnt(4) lgkmcnt(8)
	v_mfma_f32_16x16x32_bf16 v[6:9], v[44:47], v[40:43], v[6:9]
	v_mfma_f32_16x16x32_bf16 v[2:5], v[48:51], v[40:43], v[2:5]
	global_load_dwordx4 v[40:43], v[38:39], off offset:640
	ds_read_b128 v[44:47], v20 offset:640
	ds_read_b128 v[48:51], v20 offset:33664
	s_waitcnt vmcnt(4) lgkmcnt(8)
	v_mfma_f32_16x16x32_bf16 v[6:9], v[62:65], v[52:55], v[6:9]
	v_mfma_f32_16x16x32_bf16 v[2:5], v[70:73], v[52:55], v[2:5]
	global_load_dwordx4 v[52:55], v[38:39], off offset:704
	ds_read_b128 v[62:65], v20 offset:704
	ds_read_b128 v[70:73], v20 offset:33728
	s_waitcnt vmcnt(4) lgkmcnt(8)
	v_mfma_f32_16x16x32_bf16 v[6:9], v[86:89], v[82:85], v[6:9]
	v_mfma_f32_16x16x32_bf16 v[2:5], v[94:97], v[82:85], v[2:5]
	global_load_dwordx4 v[82:85], v[38:39], off offset:768
	ds_read_b128 v[86:89], v20 offset:768
	ds_read_b128 v[94:97], v20 offset:33792
	s_waitcnt vmcnt(4) lgkmcnt(8)
	v_mfma_f32_16x16x32_bf16 v[6:9], v[130:133], v[102:105], v[6:9]
	v_mfma_f32_16x16x32_bf16 v[2:5], v[134:137], v[102:105], v[2:5]
	global_load_dwordx4 v[102:105], v[38:39], off offset:832
	ds_read_b128 v[130:133], v20 offset:832
	ds_read_b128 v[134:137], v20 offset:33856
	s_waitcnt vmcnt(4) lgkmcnt(8)
	v_mfma_f32_16x16x32_bf16 v[6:9], v[142:145], v[138:141], v[6:9]
	v_mfma_f32_16x16x32_bf16 v[2:5], v[148:151], v[138:141], v[2:5]
	global_load_dwordx4 v[138:141], v[38:39], off offset:896
	ds_read_b128 v[142:145], v20 offset:896
	ds_read_b128 v[148:151], v20 offset:33920
	s_waitcnt vmcnt(4) lgkmcnt(8)
	v_mfma_f32_16x16x32_bf16 v[6:9], v[44:47], v[40:43], v[6:9]
	v_mfma_f32_16x16x32_bf16 v[2:5], v[48:51], v[40:43], v[2:5]
	global_load_dwordx4 v[40:43], v[38:39], off offset:960
	ds_read_b128 v[44:47], v20 offset:960
	ds_read_b128 v[48:51], v20 offset:33984
	s_waitcnt vmcnt(4) lgkmcnt(8)
	v_mfma_f32_16x16x32_bf16 v[6:9], v[62:65], v[52:55], v[6:9]
	v_mfma_f32_16x16x32_bf16 v[2:5], v[70:73], v[52:55], v[2:5]
	global_load_dwordx4 v[52:55], v[38:39], off offset:1024
	ds_read_b128 v[62:65], v20 offset:1024
	ds_read_b128 v[70:73], v20 offset:34048
	s_waitcnt vmcnt(4) lgkmcnt(8)
	v_mfma_f32_16x16x32_bf16 v[6:9], v[86:89], v[82:85], v[6:9]
	v_mfma_f32_16x16x32_bf16 v[2:5], v[94:97], v[82:85], v[2:5]
	global_load_dwordx4 v[82:85], v[38:39], off offset:1088
	ds_read_b128 v[86:89], v20 offset:1088
	ds_read_b128 v[94:97], v20 offset:34112
	s_waitcnt vmcnt(4) lgkmcnt(8)
	v_mfma_f32_16x16x32_bf16 v[6:9], v[130:133], v[102:105], v[6:9]
	v_mfma_f32_16x16x32_bf16 v[2:5], v[134:137], v[102:105], v[2:5]
	global_load_dwordx4 v[102:105], v[38:39], off offset:1152
	ds_read_b128 v[130:133], v20 offset:1152
	ds_read_b128 v[134:137], v20 offset:34176
	s_waitcnt vmcnt(4) lgkmcnt(8)
	v_mfma_f32_16x16x32_bf16 v[6:9], v[142:145], v[138:141], v[6:9]
	v_mfma_f32_16x16x32_bf16 v[2:5], v[148:151], v[138:141], v[2:5]
	global_load_dwordx4 v[138:141], v[38:39], off offset:1216
	ds_read_b128 v[142:145], v20 offset:1216
	ds_read_b128 v[148:151], v20 offset:34240
	s_waitcnt vmcnt(4) lgkmcnt(8)
	v_mfma_f32_16x16x32_bf16 v[6:9], v[44:47], v[40:43], v[6:9]
	v_mfma_f32_16x16x32_bf16 v[2:5], v[48:51], v[40:43], v[2:5]
	global_load_dwordx4 v[40:43], v[38:39], off offset:1280
	ds_read_b128 v[44:47], v20 offset:1280
	ds_read_b128 v[48:51], v20 offset:34304
	s_waitcnt vmcnt(4) lgkmcnt(8)
; __device__ __forceinline__ float sigmoidf_(float x) { return 1.f / (1.f + expf(-x)); }
; __device__ __forceinline__ void gates_tiles(const Frame& F, int l, int wg0) {
;     ...
;     for (int rt = gw; rt < T / 16; rt += NGW) {
;         f32x4 a0 = {0.f, 0.f, 0.f, 0.f}, a1 = {0.f, 0.f, 0.f, 0.f};
;         const bf16* ap = H + (size_t)(16 * rt + fr) * D + 8 * fq; const bf16* bp = WG + (size_t)fr * D + 8 * fq;
; #pragma unroll 8
;         for (int ks = 0; ks < 32; ++ks) { const bf16x8 a = *(const bf16x8*)(ap + 32 * ks), b0 = *(const bf16x8*)(bp + 32 * ks), b1 = *(const bf16x8*)(bp + 16 * D + 32 * ks);
;             a0 = __builtin_amdgcn_mfma_f32_16x16x32_bf16(b0, a, a0, 0, 0, 0); a1 = __builtin_amdgcn_mfma_f32_16x16x32_bf16(b1, a, a1, 0, 0, 0); }
;         float* ng = (float*)(F.ws + WS_NG) + (size_t)(16 * rt + fr) * 24;
; #pragma unroll
;         for (int j = 0; j < 4; ++j) { ng[4 * fq + j] = sigmoidf_(a0[j]); if (fq < 2) ng[16 + 4 * fq + j] = sigmoidf_(a1[j]); }
	v_mfma_f32_16x16x32_bf16 v[6:9], v[62:65], v[52:55], v[6:9]
	v_mfma_f32_16x16x32_bf16 v[2:5], v[70:73], v[52:55], v[2:5]
	global_load_dwordx4 v[52:55], v[38:39], off offset:1344
	ds_read_b128 v[62:65], v20 offset:1344
	ds_read_b128 v[70:73], v20 offset:34368
	s_waitcnt vmcnt(4) lgkmcnt(8)
	v_mfma_f32_16x16x32_bf16 v[6:9], v[86:89], v[82:85], v[6:9]
	v_mfma_f32_16x16x32_bf16 v[2:5], v[94:97], v[82:85], v[2:5]
	global_load_dwordx4 v[82:85], v[38:39], off offset:1408
	ds_read_b128 v[86:89], v20 offset:1408
	ds_read_b128 v[94:97], v20 offset:34432
	s_waitcnt vmcnt(4) lgkmcnt(8)
	v_mfma_f32_16x16x32_bf16 v[6:9], v[130:133], v[102:105], v[6:9]
	v_mfma_f32_16x16x32_bf16 v[2:5], v[134:137], v[102:105], v[2:5]
	global_load_dwordx4 v[102:105], v[38:39], off offset:1472
	ds_read_b128 v[130:133], v20 offset:1472
	ds_read_b128 v[134:137], v20 offset:34496
	s_waitcnt vmcnt(4) lgkmcnt(8)
	v_mfma_f32_16x16x32_bf16 v[6:9], v[142:145], v[138:141], v[6:9]
	v_mfma_f32_16x16x32_bf16 v[2:5], v[148:151], v[138:141], v[2:5]
	global_load_dwordx4 v[138:141], v[38:39], off offset:1536
	ds_read_b128 v[142:145], v20 offset:1536
	ds_read_b128 v[148:151], v20 offset:34560
	s_waitcnt vmcnt(4) lgkmcnt(8)
	v_mfma_f32_16x16x32_bf16 v[6:9], v[44:47], v[40:43], v[6:9]
	v_mfma_f32_16x16x32_bf16 v[2:5], v[48:51], v[40:43], v[2:5]
	global_load_dwordx4 v[40:43], v[38:39], off offset:1600
	ds_read_b128 v[44:47], v20 offset:1600
	ds_read_b128 v[48:51], v20 offset:34624
	s_waitcnt vmcnt(4) lgkmcnt(8)
	v_mfma_f32_16x16x32_bf16 v[6:9], v[62:65], v[52:55], v[6:9]
	v_mfma_f32_16x16x32_bf16 v[2:5], v[70:73], v[52:55], v[2:5]
	global_load_dwordx4 v[52:55], v[38:39], off offset:1664
	ds_read_b128 v[62:65], v20 offset:1664
	ds_read_b128 v[70:73], v20 offset:34688
	s_waitcnt vmcnt(4) lgkmcnt(8)
	v_mfma_f32_16x16x32_bf16 v[6:9], v[86:89], v[82:85], v[6:9]
	v_mfma_f32_16x16x32_bf16 v[2:5], v[94:97], v[82:85], v[2:5]
	global_load_dwordx4 v[82:85], v[38:39], off offset:1728
	ds_read_b128 v[86:89], v20 offset:1728
	ds_read_b128 v[94:97], v20 offset:34752
	s_waitcnt vmcnt(4) lgkmcnt(8)
	v_mfma_f32_16x16x32_bf16 v[6:9], v[130:133], v[102:105], v[6:9]
	v_mfma_f32_16x16x32_bf16 v[2:5], v[134:137], v[102:105], v[2:5]
	global_load_dwordx4 v[102:105], v[38:39], off offset:1792
	ds_read_b128 v[130:133], v20 offset:1792
	ds_read_b128 v[134:137], v20 offset:34816
	s_waitcnt vmcnt(4) lgkmcnt(8)
	v_mfma_f32_16x16x32_bf16 v[6:9], v[142:145], v[138:141], v[6:9]
	v_mfma_f32_16x16x32_bf16 v[2:5], v[148:151], v[138:141], v[2:5]
	global_load_dwordx4 v[138:141], v[38:39], off offset:1856
	ds_read_b128 v[142:145], v20 offset:1856
	ds_read_b128 v[148:151], v20 offset:34880
	s_waitcnt vmcnt(4) lgkmcnt(8)
	v_mfma_f32_16x16x32_bf16 v[6:9], v[44:47], v[40:43], v[6:9]
	v_mfma_f32_16x16x32_bf16 v[2:5], v[48:51], v[40:43], v[2:5]
	global_load_dwordx4 v[40:43], v[38:39], off offset:1920
	ds_read_b128 v[44:47], v20 offset:1920
	ds_read_b128 v[48:51], v20 offset:34944
	s_waitcnt vmcnt(4) lgkmcnt(8)
	v_mfma_f32_16x16x32_bf16 v[6:9], v[62:65], v[52:55], v[6:9]
	v_mfma_f32_16x16x32_bf16 v[2:5], v[70:73], v[52:55], v[2:5]
	global_load_dwordx4 v[52:55], v[38:39], off offset:1984
	ds_read_b128 v[62:65], v20 offset:1984
	ds_read_b128 v[70:73], v20 offset:35008
	s_waitcnt vmcnt(4) lgkmcnt(8)
	v_mfma_f32_16x16x32_bf16 v[6:9], v[86:89], v[82:85], v[6:9]
	v_mfma_f32_16x16x32_bf16 v[2:5], v[94:97], v[82:85], v[2:5]
	s_waitcnt vmcnt(3) lgkmcnt(6)
	v_mfma_f32_16x16x32_bf16 v[6:9], v[130:133], v[102:105], v[6:9]
	v_mfma_f32_16x16x32_bf16 v[2:5], v[134:137], v[102:105], v[2:5]
	s_waitcnt vmcnt(2) lgkmcnt(4)
	v_mfma_f32_16x16x32_bf16 v[6:9], v[142:145], v[138:141], v[6:9]
	v_mfma_f32_16x16x32_bf16 v[2:5], v[148:151], v[138:141], v[2:5]
	s_waitcnt vmcnt(1) lgkmcnt(2)
	v_mfma_f32_16x16x32_bf16 v[6:9], v[44:47], v[40:43], v[6:9]
	v_mfma_f32_16x16x32_bf16 v[2:5], v[48:51], v[40:43], v[2:5]
	s_waitcnt vmcnt(0) lgkmcnt(0)
	v_mfma_f32_16x16x32_bf16 v[6:9], v[62:65], v[52:55], v[6:9]
	v_mfma_f32_16x16x32_bf16 v[2:5], v[70:73], v[52:55], v[2:5]
	s_nop 0
	s_nop 4
	v_mul_f32_e32 v1, 0xbfb8aa3b, v6
	v_rndne_f32_e32 v15, v1
	v_sub_f32_e32 v18, v1, v15
	v_fma_f32 v1, v6, s83, -v1
	v_fmac_f32_e32 v1, 0xb2a5705f, v6
	v_add_f32_e32 v1, v18, v1
	v_cvt_i32_f32_e32 v15, v15
	v_exp_f32_e32 v1, v1
	v_cmp_nlt_f32_e32 vcc, s92, v6
	v_lshl_or_b32 v18, s3, 4, v24
	v_ldexp_f32 v1, v1, v15
	v_cndmask_b32_e32 v1, 0, v1, vcc
	v_cmp_ngt_f32_e32 vcc, s93, v6
	s_nop 1
	v_cndmask_b32_e32 v1, v230, v1, vcc
	v_add_f32_e32 v1, 1.0, v1
	v_div_scale_f32 v6, s[4:5], v1, v1, 1.0
	v_rcp_f32_e32 v15, v6
	s_movk_i32 s4, 0x60
	v_fma_f32 v19, -v6, v15, 1.0
	v_fmac_f32_e32 v15, v19, v15
	v_div_scale_f32 v19, vcc, 1.0, v1, 1.0
	v_mul_f32_e32 v20, v19, v15
	v_fma_f32 v21, -v6, v20, v19
	v_fmac_f32_e32 v20, v21, v15
	v_fma_f32 v6, -v6, v20, v19
	v_div_fmas_f32 v6, v6, v15, v20
	v_div_fixup_f32 v1, v6, v1, 1.0
	v_mad_i64_i32 v[18:19], s[4:5], v18, s4, v[10:11]
	v_mov_b64_e32 v[20:21], 4
	global_store_dword v[18:19], v1, off
	s_and_saveexec_b64 s[14:15], s[0:1]
	s_cbranch_execz .LBB0_1343
	v_mul_f32_e32 v1, 0xbfb8aa3b, v2
	v_rndne_f32_e32 v6, v1
	v_sub_f32_e32 v15, v1, v6
	v_fma_f32 v1, v2, s83, -v1
	v_fmac_f32_e32 v1, 0xb2a5705f, v2
	v_add_f32_e32 v1, v15, v1
	v_exp_f32_e32 v1, v1
	v_cvt_i32_f32_e32 v6, v6
	v_cmp_nlt_f32_e32 vcc, s92, v2
	v_ldexp_f32 v1, v1, v6
	s_nop 0
	v_cndmask_b32_e32 v1, 0, v1, vcc
	v_cmp_ngt_f32_e32 vcc, s93, v2
	s_nop 1
	v_cndmask_b32_e32 v1, v230, v1, vcc
	v_add_f32_e32 v1, 1.0, v1
	v_div_scale_f32 v2, s[4:5], v1, v1, 1.0
	v_rcp_f32_e32 v6, v2
	s_nop 0
	v_fma_f32 v15, -v2, v6, 1.0
	v_fmac_f32_e32 v6, v15, v6
	v_div_scale_f32 v15, vcc, 1.0, v1, 1.0
	v_mul_f32_e32 v20, v15, v6
	v_fma_f32 v21, -v2, v20, v15
	v_fmac_f32_e32 v20, v21, v6
	v_fma_f32 v2, -v2, v20, v15
	v_div_fmas_f32 v2, v2, v6, v20
	v_div_fixup_f32 v1, v2, v1, 1.0
	global_store_dword v[18:19], v1, off offset:64
	v_mul_f32_e32 v1, 0xbfb8aa3b, v7
	v_rndne_f32_e32 v2, v1
	v_sub_f32_e32 v6, v1, v2
	v_fma_f32 v1, v7, s83, -v1
	v_fmac_f32_e32 v1, 0xb2a5705f, v7
	v_add_f32_e32 v1, v6, v1
	v_exp_f32_e32 v1, v1
	v_cvt_i32_f32_e32 v2, v2
	v_cmp_nlt_f32_e32 vcc, s92, v7
	v_ldexp_f32 v1, v1, v2
	s_nop 0
	v_cndmask_b32_e32 v1, 0, v1, vcc
	v_cmp_ngt_f32_e32 vcc, s93, v7
	s_nop 1
	v_cndmask_b32_e32 v1, v230, v1, vcc
	v_add_f32_e32 v1, 1.0, v1
	v_div_scale_f32 v2, s[4:5], v1, v1, 1.0
	v_rcp_f32_e32 v6, v2
	s_nop 0
	v_fma_f32 v7, -v2, v6, 1.0
	v_fmac_f32_e32 v6, v7, v6
	v_div_scale_f32 v7, vcc, 1.0, v1, 1.0
	v_mul_f32_e32 v15, v7, v6
	v_fma_f32 v20, -v2, v15, v7
	v_fmac_f32_e32 v15, v20, v6
	v_fma_f32 v2, -v2, v15, v7
	v_div_fmas_f32 v2, v2, v6, v15
	v_div_fixup_f32 v1, v2, v1, 1.0
	v_mov_b64_e32 v[20:21], 0x44
	v_mov_b32_e32 v7, v3
	global_store_dword v[18:19], v1, off offset:4
